# v54 + input-projection (P2) rotary epilogue: 16 rope-table loads hoisted into dedicated registers with counted vmcnt instead of 8 serialized load/vmcnt(0)/store groups per tile
# speedup vs baseline: 1.0057x; 1.0046x over previous
; __device__ __forceinline__ u32x2 pack4(f32x4 v) { u32x2 w; w.x = cvtpk(v[0], v[1]); w.y = cvtpk(v[2], v[3]); return w; }
;     __device__ __forceinline__ void operator()(const Acc& acc, const Unit& u, int wr, int wc, int fr, int fq) const {
;     ...
;                 for (int m = 0; m < 4; ++m) {
;                     const int row = rowb + ai * 128 + m * 16;
;                     f32x4 v[2][2];
; #pragma unroll
;                     for (int bj = 0; bj < 2; ++bj) { v[bj][0] = acc[ai][bj][m][0]; v[bj][1] = acc[ai][bj][m][1]; }
;                     if (rope) { const f32x4 cs = *(const f32x4*)(ropeP + (size_t)row * 32 + 4 * fq), sn = *(const f32x4*)(ropeP + (size_t)row * 32 + 16 + 4 * fq);
; #pragma unroll
;                         for (int bj = 0; bj < 2; ++bj) { const f32x4 x1 = v[bj][0], x2 = v[bj][1]; v[bj][0] = x1 * cs - x2 * sn; v[bj][1] = x2 * cs + x1 * sn; } }
;                     bf16_t* rp = dst + (size_t)row * ldo + wc * 32 + 4 * fq;
; #pragma unroll
;                     for (int bj = 0; bj < 2; ++bj)
; #pragma unroll
;                         for (int n = 0; n < 2; ++n) *(u32x2*)(rp + bj * 128 + n * 16) = pack4(v[bj][n]);
.LBB0_548:
	s_and_b64 s[48:49], s[34:35], s[48:49]
	v_cndmask_b32_e64 v4, 0, 1, s[48:49]
	v_cmp_ne_u32_e64 s[4:5], 1, v4
	s_andn2_b64 vcc, exec, s[48:49]
	v_lshlrev_b32_e32 v4, 2, v166
	s_cbranch_vccnz .LBB0_550
	v_lshlrev_b64 v[6:7], 7, v[2:3]
	v_lshl_add_u64 v[6:7], s[20:21], 0, v[6:7]
	s_waitcnt lgkmcnt(0)
	v_mov_b32_e32 v5, v167
	v_lshl_add_u64 v[10:11], v[6:7], 0, v[4:5]
	v_lshlrev_b64 v[242:243], 7, v[2:3]
	v_lshl_add_u64 v[242:243], s[20:21], 0, v[242:243]
	v_mov_b32_e32 v5, v167
	v_lshl_add_u64 v[242:243], v[242:243], 0, v[4:5]
	v_mov_b32_e32 v255, 0
	global_load_dwordx4 v[188:191], v[242:243], off offset:64
	global_load_dwordx4 v[192:195], v[242:243], off
	v_mov_b32_e32 v254, 0x800
	v_lshl_add_u64 v[30:31], v[242:243], 0, v[254:255]
	global_load_dwordx4 v[196:199], v[30:31], off offset:64
	global_load_dwordx4 v[200:203], v[30:31], off
	v_mov_b32_e32 v254, 0x1000
	v_lshl_add_u64 v[30:31], v[242:243], 0, v[254:255]
	global_load_dwordx4 v[206:209], v[30:31], off offset:64
	global_load_dwordx4 v[210:213], v[30:31], off
	v_mov_b32_e32 v254, 0x1800
	v_lshl_add_u64 v[30:31], v[242:243], 0, v[254:255]
	global_load_dwordx4 v[214:217], v[30:31], off offset:64
	global_load_dwordx4 v[218:221], v[30:31], off
	v_mov_b32_e32 v254, 0x4000
	v_lshl_add_u64 v[30:31], v[242:243], 0, v[254:255]
	global_load_dwordx4 v[222:225], v[30:31], off offset:64
	global_load_dwordx4 v[226:229], v[30:31], off
	v_mov_b32_e32 v254, 0x4800
	v_lshl_add_u64 v[30:31], v[242:243], 0, v[254:255]
	global_load_dwordx4 v[230:233], v[30:31], off offset:64
	global_load_dwordx4 v[234:237], v[30:31], off
	v_mov_b32_e32 v254, 0x5000
	v_lshl_add_u64 v[30:31], v[242:243], 0, v[254:255]
	global_load_dwordx4 v[238:241], v[30:31], off offset:64
	global_load_dwordx4 v[246:249], v[30:31], off
	v_mov_b32_e32 v254, 0x5800
	v_lshl_add_u64 v[30:31], v[242:243], 0, v[254:255]
	global_load_dwordx4 v[250:253], v[30:31], off offset:64
	global_load_dwordx4 v[174:177], v[30:31], off
	s_nop 0
	s_waitcnt vmcnt(14)
	v_pk_mul_f32 v[14:15], v[156:157], v[190:191]
	v_pk_mul_f32 v[16:17], v[154:155], v[188:189]
	v_pk_mul_f32 v[18:19], v[160:161], v[190:191]
	v_pk_mul_f32 v[20:21], v[158:159], v[188:189]
	v_pk_mul_f32 v[22:23], v[148:149], v[190:191]
	v_pk_mul_f32 v[24:25], v[146:147], v[188:189]
	v_pk_mul_f32 v[8:9], v[152:153], v[190:191]
	v_pk_mul_f32 v[6:7], v[150:151], v[188:189]
	v_pk_fma_f32 v[160:161], v[160:161], v[194:195], v[14:15] neg_lo:[0,0,1] neg_hi:[0,0,1]
	v_pk_fma_f32 v[158:159], v[158:159], v[192:193], v[16:17] neg_lo:[0,0,1] neg_hi:[0,0,1]
	v_pk_fma_f32 v[156:157], v[156:157], v[194:195], v[18:19]
	v_pk_fma_f32 v[154:155], v[154:155], v[192:193], v[20:21]
	v_pk_fma_f32 v[152:153], v[152:153], v[194:195], v[22:23] neg_lo:[0,0,1] neg_hi:[0,0,1]
	v_pk_fma_f32 v[150:151], v[150:151], v[192:193], v[24:25] neg_lo:[0,0,1] neg_hi:[0,0,1]
	v_pk_fma_f32 v[148:149], v[148:149], v[194:195], v[8:9]
	v_pk_fma_f32 v[146:147], v[146:147], v[192:193], v[6:7]
.LBB0_550:
	s_lshl_b32 s7, s65, 1
	s_add_u32 s46, s46, s7
	s_addc_u32 s47, s47, 0
	v_lshlrev_b32_e32 v166, 1, v166
	v_lshl_add_u64 v[6:7], s[46:47], 0, v[166:167]
	v_mad_i64_i32 v[8:9], s[46:47], s6, v2, 0
	v_lshl_add_u64 v[8:9], v[8:9], 1, v[6:7]
	v_cvt_pk_bf16_f32 v10, v158, v159
	v_cvt_pk_bf16_f32 v11, v160, v161
	global_store_dwordx2 v[8:9], v[10:11], off
	v_cvt_pk_bf16_f32 v10, v154, v155
	v_cvt_pk_bf16_f32 v11, v156, v157
	global_store_dwordx2 v[8:9], v[10:11], off offset:32
	v_cvt_pk_bf16_f32 v10, v150, v151
	v_cvt_pk_bf16_f32 v11, v152, v153
	global_store_dwordx2 v[8:9], v[10:11], off offset:256
	v_cvt_pk_bf16_f32 v10, v146, v147
	v_cvt_pk_bf16_f32 v11, v148, v149
	global_store_dwordx2 v[8:9], v[10:11], off offset:288
	v_or_b32_e32 v8, 16, v2
	s_and_b64 vcc, exec, s[4:5]
	v_ashrrev_i32_e32 v9, 31, v8
	s_cbranch_vccnz .LBB0_552
	v_lshlrev_b64 v[10:11], 7, v[8:9]
	v_lshl_add_u64 v[10:11], s[20:21], 0, v[10:11]
	s_waitcnt lgkmcnt(0)
	v_mov_b32_e32 v5, v167
	v_lshl_add_u64 v[14:15], v[10:11], 0, v[4:5]
	s_nop 0
	s_waitcnt vmcnt(16)
	v_pk_mul_f32 v[18:19], v[140:141], v[198:199]
	v_pk_mul_f32 v[20:21], v[138:139], v[196:197]
	v_pk_mul_f32 v[22:23], v[144:145], v[198:199]
	v_pk_mul_f32 v[24:25], v[142:143], v[196:197]
	v_pk_mul_f32 v[26:27], v[132:133], v[198:199]
	v_pk_mul_f32 v[28:29], v[130:131], v[196:197]
	v_pk_mul_f32 v[12:13], v[136:137], v[198:199]
	v_pk_mul_f32 v[10:11], v[134:135], v[196:197]
	v_pk_fma_f32 v[144:145], v[144:145], v[202:203], v[18:19] neg_lo:[0,0,1] neg_hi:[0,0,1]
	v_pk_fma_f32 v[142:143], v[142:143], v[200:201], v[20:21] neg_lo:[0,0,1] neg_hi:[0,0,1]
	v_pk_fma_f32 v[140:141], v[140:141], v[202:203], v[22:23]
	v_pk_fma_f32 v[138:139], v[138:139], v[200:201], v[24:25]
	v_pk_fma_f32 v[136:137], v[136:137], v[202:203], v[26:27] neg_lo:[0,0,1] neg_hi:[0,0,1]
	v_pk_fma_f32 v[134:135], v[134:135], v[200:201], v[28:29] neg_lo:[0,0,1] neg_hi:[0,0,1]
	v_pk_fma_f32 v[132:133], v[132:133], v[202:203], v[12:13]
	v_pk_fma_f32 v[130:131], v[130:131], v[200:201], v[10:11]
; __device__ __forceinline__ u32x2 pack4(f32x4 v) { u32x2 w; w.x = cvtpk(v[0], v[1]); w.y = cvtpk(v[2], v[3]); return w; }
;     __device__ __forceinline__ void operator()(const Acc& acc, const Unit& u, int wr, int wc, int fr, int fq) const {
;     ...
;                 for (int m = 0; m < 4; ++m) {
;                     const int row = rowb + ai * 128 + m * 16;
;                     f32x4 v[2][2];
; #pragma unroll
;                     for (int bj = 0; bj < 2; ++bj) { v[bj][0] = acc[ai][bj][m][0]; v[bj][1] = acc[ai][bj][m][1]; }
;                     if (rope) { const f32x4 cs = *(const f32x4*)(ropeP + (size_t)row * 32 + 4 * fq), sn = *(const f32x4*)(ropeP + (size_t)row * 32 + 16 + 4 * fq);
; #pragma unroll
;                         for (int bj = 0; bj < 2; ++bj) { const f32x4 x1 = v[bj][0], x2 = v[bj][1]; v[bj][0] = x1 * cs - x2 * sn; v[bj][1] = x2 * cs + x1 * sn; } }
;                     bf16_t* rp = dst + (size_t)row * ldo + wc * 32 + 4 * fq;
; #pragma unroll
;                     for (int bj = 0; bj < 2; ++bj)
; #pragma unroll
;                         for (int n = 0; n < 2; ++n) *(u32x2*)(rp + bj * 128 + n * 16) = pack4(v[bj][n]);
.LBB0_552:
	v_mad_i64_i32 v[8:9], s[46:47], s6, v8, 0
	v_lshl_add_u64 v[8:9], v[8:9], 1, v[6:7]
	v_cvt_pk_bf16_f32 v10, v142, v143
	v_cvt_pk_bf16_f32 v11, v144, v145
	global_store_dwordx2 v[8:9], v[10:11], off
	v_cvt_pk_bf16_f32 v10, v138, v139
	v_cvt_pk_bf16_f32 v11, v140, v141
	global_store_dwordx2 v[8:9], v[10:11], off offset:32
	v_cvt_pk_bf16_f32 v10, v134, v135
	v_cvt_pk_bf16_f32 v11, v136, v137
	global_store_dwordx2 v[8:9], v[10:11], off offset:256
	v_cvt_pk_bf16_f32 v10, v130, v131
	v_cvt_pk_bf16_f32 v11, v132, v133
	global_store_dwordx2 v[8:9], v[10:11], off offset:288
	v_or_b32_e32 v8, 32, v2
	s_and_b64 vcc, exec, s[4:5]
	v_ashrrev_i32_e32 v9, 31, v8
	s_cbranch_vccnz .LBB0_554
	v_lshlrev_b64 v[10:11], 7, v[8:9]
	v_lshl_add_u64 v[10:11], s[20:21], 0, v[10:11]
	s_waitcnt lgkmcnt(0)
	v_mov_b32_e32 v5, v167
	v_lshl_add_u64 v[14:15], v[10:11], 0, v[4:5]
	s_nop 0
	s_waitcnt vmcnt(18)
	v_pk_mul_f32 v[18:19], v[124:125], v[208:209]
	v_pk_mul_f32 v[20:21], v[122:123], v[206:207]
	v_pk_mul_f32 v[22:23], v[128:129], v[208:209]
	v_pk_mul_f32 v[24:25], v[126:127], v[206:207]
	v_pk_mul_f32 v[26:27], v[116:117], v[208:209]
	v_pk_mul_f32 v[28:29], v[114:115], v[206:207]
	v_pk_mul_f32 v[12:13], v[120:121], v[208:209]
	v_pk_mul_f32 v[10:11], v[118:119], v[206:207]
	v_pk_fma_f32 v[128:129], v[128:129], v[212:213], v[18:19] neg_lo:[0,0,1] neg_hi:[0,0,1]
	v_pk_fma_f32 v[126:127], v[126:127], v[210:211], v[20:21] neg_lo:[0,0,1] neg_hi:[0,0,1]
	v_pk_fma_f32 v[124:125], v[124:125], v[212:213], v[22:23]
	v_pk_fma_f32 v[122:123], v[122:123], v[210:211], v[24:25]
	v_pk_fma_f32 v[120:121], v[120:121], v[212:213], v[26:27] neg_lo:[0,0,1] neg_hi:[0,0,1]
	v_pk_fma_f32 v[118:119], v[118:119], v[210:211], v[28:29] neg_lo:[0,0,1] neg_hi:[0,0,1]
	v_pk_fma_f32 v[116:117], v[116:117], v[212:213], v[12:13]
	v_pk_fma_f32 v[114:115], v[114:115], v[210:211], v[10:11]
.LBB0_554:
	v_mad_i64_i32 v[8:9], s[46:47], s6, v8, 0
	v_lshl_add_u64 v[8:9], v[8:9], 1, v[6:7]
	v_cvt_pk_bf16_f32 v10, v126, v127
	v_cvt_pk_bf16_f32 v11, v128, v129
	global_store_dwordx2 v[8:9], v[10:11], off
	v_cvt_pk_bf16_f32 v10, v122, v123
	v_cvt_pk_bf16_f32 v11, v124, v125
	global_store_dwordx2 v[8:9], v[10:11], off offset:32
	v_cvt_pk_bf16_f32 v10, v118, v119
	v_cvt_pk_bf16_f32 v11, v120, v121
	global_store_dwordx2 v[8:9], v[10:11], off offset:256
	v_cvt_pk_bf16_f32 v10, v114, v115
	v_cvt_pk_bf16_f32 v11, v116, v117
	global_store_dwordx2 v[8:9], v[10:11], off offset:288
	v_or_b32_e32 v8, 48, v2
	s_and_b64 vcc, exec, s[4:5]
	v_ashrrev_i32_e32 v9, 31, v8
	s_cbranch_vccnz .LBB0_556
	v_lshlrev_b64 v[10:11], 7, v[8:9]
	v_lshl_add_u64 v[10:11], s[20:21], 0, v[10:11]
	s_waitcnt lgkmcnt(0)
	v_mov_b32_e32 v5, v167
	v_lshl_add_u64 v[14:15], v[10:11], 0, v[4:5]
	s_nop 0
	s_waitcnt vmcnt(20)
	v_pk_mul_f32 v[18:19], v[108:109], v[216:217]
	v_pk_mul_f32 v[20:21], v[106:107], v[214:215]
	v_pk_mul_f32 v[22:23], v[112:113], v[216:217]
	v_pk_mul_f32 v[24:25], v[110:111], v[214:215]
	v_pk_mul_f32 v[26:27], v[100:101], v[216:217]
	v_pk_mul_f32 v[28:29], v[98:99], v[214:215]
	v_pk_mul_f32 v[12:13], v[104:105], v[216:217]
	v_pk_mul_f32 v[10:11], v[102:103], v[214:215]
	v_pk_fma_f32 v[112:113], v[112:113], v[220:221], v[18:19] neg_lo:[0,0,1] neg_hi:[0,0,1]
	v_pk_fma_f32 v[110:111], v[110:111], v[218:219], v[20:21] neg_lo:[0,0,1] neg_hi:[0,0,1]
	v_pk_fma_f32 v[108:109], v[108:109], v[220:221], v[22:23]
	v_pk_fma_f32 v[106:107], v[106:107], v[218:219], v[24:25]
	v_pk_fma_f32 v[104:105], v[104:105], v[220:221], v[26:27] neg_lo:[0,0,1] neg_hi:[0,0,1]
	v_pk_fma_f32 v[102:103], v[102:103], v[218:219], v[28:29] neg_lo:[0,0,1] neg_hi:[0,0,1]
	v_pk_fma_f32 v[100:101], v[100:101], v[220:221], v[12:13]
	v_pk_fma_f32 v[98:99], v[98:99], v[218:219], v[10:11]
.LBB0_556:
	v_mad_i64_i32 v[8:9], s[46:47], s6, v8, 0
	v_lshl_add_u64 v[8:9], v[8:9], 1, v[6:7]
	v_cvt_pk_bf16_f32 v10, v110, v111
	v_cvt_pk_bf16_f32 v11, v112, v113
	global_store_dwordx2 v[8:9], v[10:11], off
	v_cvt_pk_bf16_f32 v10, v106, v107
	v_cvt_pk_bf16_f32 v11, v108, v109
	global_store_dwordx2 v[8:9], v[10:11], off offset:32
	v_cvt_pk_bf16_f32 v10, v102, v103
	v_cvt_pk_bf16_f32 v11, v104, v105
	global_store_dwordx2 v[8:9], v[10:11], off offset:256
	v_cvt_pk_bf16_f32 v10, v98, v99
	v_cvt_pk_bf16_f32 v11, v100, v101
	global_store_dwordx2 v[8:9], v[10:11], off offset:288
	v_add_u32_e32 v8, 0x80, v2
	s_and_b64 vcc, exec, s[4:5]
	v_ashrrev_i32_e32 v9, 31, v8
	s_cbranch_vccnz .LBB0_558
	v_lshlrev_b64 v[10:11], 7, v[8:9]
	v_lshl_add_u64 v[10:11], s[20:21], 0, v[10:11]
	s_waitcnt lgkmcnt(0)
	v_mov_b32_e32 v5, v167
	v_lshl_add_u64 v[14:15], v[10:11], 0, v[4:5]
	s_nop 0
	s_waitcnt vmcnt(22)
	v_pk_mul_f32 v[18:19], v[92:93], v[224:225]
	v_pk_mul_f32 v[20:21], v[90:91], v[222:223]
	v_pk_mul_f32 v[22:23], v[96:97], v[224:225]
	v_pk_mul_f32 v[24:25], v[94:95], v[222:223]
	v_pk_mul_f32 v[26:27], v[84:85], v[224:225]
	v_pk_mul_f32 v[28:29], v[82:83], v[222:223]
	v_pk_mul_f32 v[12:13], v[88:89], v[224:225]
	v_pk_mul_f32 v[10:11], v[86:87], v[222:223]
	v_pk_fma_f32 v[96:97], v[96:97], v[228:229], v[18:19] neg_lo:[0,0,1] neg_hi:[0,0,1]
	v_pk_fma_f32 v[94:95], v[94:95], v[226:227], v[20:21] neg_lo:[0,0,1] neg_hi:[0,0,1]
	v_pk_fma_f32 v[92:93], v[92:93], v[228:229], v[22:23]
	v_pk_fma_f32 v[90:91], v[90:91], v[226:227], v[24:25]
	v_pk_fma_f32 v[88:89], v[88:89], v[228:229], v[26:27] neg_lo:[0,0,1] neg_hi:[0,0,1]
	v_pk_fma_f32 v[86:87], v[86:87], v[226:227], v[28:29] neg_lo:[0,0,1] neg_hi:[0,0,1]
	v_pk_fma_f32 v[84:85], v[84:85], v[228:229], v[12:13]
	v_pk_fma_f32 v[82:83], v[82:83], v[226:227], v[10:11]
; __device__ __forceinline__ u32x2 pack4(f32x4 v) { u32x2 w; w.x = cvtpk(v[0], v[1]); w.y = cvtpk(v[2], v[3]); return w; }
;     __device__ __forceinline__ void operator()(const Acc& acc, const Unit& u, int wr, int wc, int fr, int fq) const {
;     ...
;                 for (int m = 0; m < 4; ++m) {
;                     const int row = rowb + ai * 128 + m * 16;
;                     f32x4 v[2][2];
; #pragma unroll
;                     for (int bj = 0; bj < 2; ++bj) { v[bj][0] = acc[ai][bj][m][0]; v[bj][1] = acc[ai][bj][m][1]; }
;                     if (rope) { const f32x4 cs = *(const f32x4*)(ropeP + (size_t)row * 32 + 4 * fq), sn = *(const f32x4*)(ropeP + (size_t)row * 32 + 16 + 4 * fq);
; #pragma unroll
;                         for (int bj = 0; bj < 2; ++bj) { const f32x4 x1 = v[bj][0], x2 = v[bj][1]; v[bj][0] = x1 * cs - x2 * sn; v[bj][1] = x2 * cs + x1 * sn; } }
;                     bf16_t* rp = dst + (size_t)row * ldo + wc * 32 + 4 * fq;
; #pragma unroll
;                     for (int bj = 0; bj < 2; ++bj)
; #pragma unroll
;                         for (int n = 0; n < 2; ++n) *(u32x2*)(rp + bj * 128 + n * 16) = pack4(v[bj][n]);
.LBB0_558:
	v_mad_i64_i32 v[8:9], s[46:47], s6, v8, 0
	v_lshl_add_u64 v[8:9], v[8:9], 1, v[6:7]
	v_cvt_pk_bf16_f32 v10, v94, v95
	v_cvt_pk_bf16_f32 v11, v96, v97
	global_store_dwordx2 v[8:9], v[10:11], off
	v_cvt_pk_bf16_f32 v10, v90, v91
	v_cvt_pk_bf16_f32 v11, v92, v93
	global_store_dwordx2 v[8:9], v[10:11], off offset:32
	v_cvt_pk_bf16_f32 v10, v86, v87
	v_cvt_pk_bf16_f32 v11, v88, v89
	global_store_dwordx2 v[8:9], v[10:11], off offset:256
	v_cvt_pk_bf16_f32 v10, v82, v83
	v_cvt_pk_bf16_f32 v11, v84, v85
	global_store_dwordx2 v[8:9], v[10:11], off offset:288
	v_add_u32_e32 v8, 0x90, v2
	s_and_b64 vcc, exec, s[4:5]
	v_ashrrev_i32_e32 v9, 31, v8
	s_cbranch_vccnz .LBB0_560
	v_lshlrev_b64 v[10:11], 7, v[8:9]
	v_lshl_add_u64 v[10:11], s[20:21], 0, v[10:11]
	s_waitcnt lgkmcnt(0)
	v_mov_b32_e32 v5, v167
	v_lshl_add_u64 v[14:15], v[10:11], 0, v[4:5]
	s_nop 0
	s_waitcnt vmcnt(24)
	v_pk_mul_f32 v[18:19], v[76:77], v[232:233]
	v_pk_mul_f32 v[20:21], v[74:75], v[230:231]
	v_pk_mul_f32 v[22:23], v[80:81], v[232:233]
	v_pk_mul_f32 v[24:25], v[78:79], v[230:231]
	v_pk_mul_f32 v[26:27], v[68:69], v[232:233]
	v_pk_mul_f32 v[28:29], v[66:67], v[230:231]
	v_pk_mul_f32 v[12:13], v[72:73], v[232:233]
	v_pk_mul_f32 v[10:11], v[70:71], v[230:231]
	v_pk_fma_f32 v[80:81], v[80:81], v[236:237], v[18:19] neg_lo:[0,0,1] neg_hi:[0,0,1]
	v_pk_fma_f32 v[78:79], v[78:79], v[234:235], v[20:21] neg_lo:[0,0,1] neg_hi:[0,0,1]
	v_pk_fma_f32 v[76:77], v[76:77], v[236:237], v[22:23]
	v_pk_fma_f32 v[74:75], v[74:75], v[234:235], v[24:25]
	v_pk_fma_f32 v[72:73], v[72:73], v[236:237], v[26:27] neg_lo:[0,0,1] neg_hi:[0,0,1]
	v_pk_fma_f32 v[70:71], v[70:71], v[234:235], v[28:29] neg_lo:[0,0,1] neg_hi:[0,0,1]
	v_pk_fma_f32 v[68:69], v[68:69], v[236:237], v[12:13]
	v_pk_fma_f32 v[66:67], v[66:67], v[234:235], v[10:11]
.LBB0_560:
	v_mad_i64_i32 v[8:9], s[46:47], s6, v8, 0
	v_lshl_add_u64 v[8:9], v[8:9], 1, v[6:7]
	v_cvt_pk_bf16_f32 v10, v78, v79
	v_cvt_pk_bf16_f32 v11, v80, v81
	global_store_dwordx2 v[8:9], v[10:11], off
	v_cvt_pk_bf16_f32 v10, v74, v75
	v_cvt_pk_bf16_f32 v11, v76, v77
	global_store_dwordx2 v[8:9], v[10:11], off offset:32
	v_cvt_pk_bf16_f32 v10, v70, v71
	v_cvt_pk_bf16_f32 v11, v72, v73
	global_store_dwordx2 v[8:9], v[10:11], off offset:256
	v_cvt_pk_bf16_f32 v10, v66, v67
	v_cvt_pk_bf16_f32 v11, v68, v69
	global_store_dwordx2 v[8:9], v[10:11], off offset:288
	v_add_u32_e32 v8, 0xa0, v2
	s_and_b64 vcc, exec, s[4:5]
	v_ashrrev_i32_e32 v9, 31, v8
	s_cbranch_vccnz .LBB0_562
	v_lshlrev_b64 v[10:11], 7, v[8:9]
	v_lshl_add_u64 v[10:11], s[20:21], 0, v[10:11]
	s_waitcnt lgkmcnt(0)
	v_mov_b32_e32 v5, v167
	v_lshl_add_u64 v[14:15], v[10:11], 0, v[4:5]
	s_nop 0
	s_waitcnt vmcnt(26)
	v_pk_mul_f32 v[18:19], v[60:61], v[240:241]
	v_pk_mul_f32 v[20:21], v[58:59], v[238:239]
	v_pk_mul_f32 v[22:23], v[64:65], v[240:241]
	v_pk_mul_f32 v[24:25], v[62:63], v[238:239]
	v_pk_mul_f32 v[26:27], v[52:53], v[240:241]
	v_pk_mul_f32 v[28:29], v[50:51], v[238:239]
	v_pk_mul_f32 v[12:13], v[56:57], v[240:241]
	v_pk_mul_f32 v[10:11], v[54:55], v[238:239]
	v_pk_fma_f32 v[64:65], v[64:65], v[248:249], v[18:19] neg_lo:[0,0,1] neg_hi:[0,0,1]
	v_pk_fma_f32 v[62:63], v[62:63], v[246:247], v[20:21] neg_lo:[0,0,1] neg_hi:[0,0,1]
	v_pk_fma_f32 v[60:61], v[60:61], v[248:249], v[22:23]
	v_pk_fma_f32 v[58:59], v[58:59], v[246:247], v[24:25]
	v_pk_fma_f32 v[56:57], v[56:57], v[248:249], v[26:27] neg_lo:[0,0,1] neg_hi:[0,0,1]
	v_pk_fma_f32 v[54:55], v[54:55], v[246:247], v[28:29] neg_lo:[0,0,1] neg_hi:[0,0,1]
	v_pk_fma_f32 v[52:53], v[52:53], v[248:249], v[12:13]
	v_pk_fma_f32 v[50:51], v[50:51], v[246:247], v[10:11]
.LBB0_562:
	v_mad_i64_i32 v[8:9], s[46:47], s6, v8, 0
	v_lshl_add_u64 v[8:9], v[8:9], 1, v[6:7]
	v_cvt_pk_bf16_f32 v10, v62, v63
	v_cvt_pk_bf16_f32 v11, v64, v65
	global_store_dwordx2 v[8:9], v[10:11], off
	v_cvt_pk_bf16_f32 v10, v58, v59
	v_cvt_pk_bf16_f32 v11, v60, v61
	global_store_dwordx2 v[8:9], v[10:11], off offset:32
	v_cvt_pk_bf16_f32 v10, v54, v55
	v_cvt_pk_bf16_f32 v11, v56, v57
	v_add_u32_e32 v2, 0xb0, v2
	global_store_dwordx2 v[8:9], v[10:11], off offset:256
	v_cvt_pk_bf16_f32 v10, v50, v51
	v_cvt_pk_bf16_f32 v11, v52, v53
	s_and_b64 vcc, exec, s[4:5]
	v_ashrrev_i32_e32 v3, 31, v2
	global_store_dwordx2 v[8:9], v[10:11], off offset:288
	s_cbranch_vccnz .LBB0_495
	v_lshlrev_b64 v[8:9], 7, v[2:3]
	v_lshl_add_u64 v[8:9], s[20:21], 0, v[8:9]
	s_waitcnt lgkmcnt(0)
	v_mov_b32_e32 v5, v167
	v_lshl_add_u64 v[4:5], v[8:9], 0, v[4:5]
	s_waitcnt vmcnt(28)
	v_pk_mul_f32 v[4:5], v[44:45], v[252:253]
	v_pk_mul_f32 v[16:17], v[42:43], v[250:251]
	v_pk_mul_f32 v[18:19], v[48:49], v[252:253]
	v_pk_mul_f32 v[20:21], v[46:47], v[250:251]
	v_pk_mul_f32 v[22:23], v[36:37], v[252:253]
	v_pk_mul_f32 v[24:25], v[34:35], v[250:251]
	v_pk_mul_f32 v[10:11], v[40:41], v[252:253]
	v_pk_mul_f32 v[8:9], v[38:39], v[250:251]
	v_pk_fma_f32 v[48:49], v[48:49], v[176:177], v[4:5] neg_lo:[0,0,1] neg_hi:[0,0,1]
	v_pk_fma_f32 v[46:47], v[46:47], v[174:175], v[16:17] neg_lo:[0,0,1] neg_hi:[0,0,1]
	v_pk_fma_f32 v[44:45], v[44:45], v[176:177], v[18:19]
	v_pk_fma_f32 v[42:43], v[42:43], v[174:175], v[20:21]
	v_pk_fma_f32 v[40:41], v[40:41], v[176:177], v[22:23] neg_lo:[0,0,1] neg_hi:[0,0,1]
	v_pk_fma_f32 v[38:39], v[38:39], v[174:175], v[24:25] neg_lo:[0,0,1] neg_hi:[0,0,1]
	v_pk_fma_f32 v[36:37], v[36:37], v[176:177], v[10:11]
	v_pk_fma_f32 v[34:35], v[34:35], v[174:175], v[8:9]
	s_branch .LBB0_495
